# k31 + the same s_setprio flips around the MFMA bursts of the L0 differential attention tile block
# baseline (speedup 1.0000x reference)
; template <int DQK, int DV, int MODE, int QPRE, bool DIFF> ...
;     ...
;             if (!QKFIRST) {
;                 const LAS unsigned char* kb = lds + bi * BUF + l32 * KST + hi * 16;
;             {
;                 const bf16x8 a0 = *(const LAS bf16x8*)(kb), a1 = *(const LAS bf16x8*)(kb + 32 * KST);
;                 if (MODE == 1) { const f32x16 z16 = {0.f, 0.f, 0.f, 0.f, 0.f, 0.f, 0.f, 0.f, 0.f, 0.f, 0.f, 0.f, 0.f, 0.f, 0.f, 0.f};
;                     s0 = __builtin_amdgcn_mfma_f32_32x32x16_bf16(a0, qf[0], z16, 0, 0, 0); s1 = __builtin_amdgcn_mfma_f32_32x32x16_bf16(a1, qf[0], z16, 0, 0, 0); }
;                 else { s0 = __builtin_amdgcn_mfma_f32_32x32x16_bf16(a0, qf[0], negm, 0, 0, 0); s1 = __builtin_amdgcn_mfma_f32_32x32x16_bf16(a1, qf[0], negm, 0, 0, 0); }
;             }
; #pragma unroll
;             for (int d0 = 1; d0 < ND0; ++d0) {
;                 const bf16x8 a0 = *(const LAS bf16x8*)(kb + d0 * 32), a1 = *(const LAS bf16x8*)(kb + 32 * KST + d0 * 32);
;                 s0 = __builtin_amdgcn_mfma_f32_32x32x16_bf16(a0, qf[d0], s0, 0, 0, 0);
;                 s1 = __builtin_amdgcn_mfma_f32_32x32x16_bf16(a1, qf[d0], s1, 0, 0, 0);
;             }
;             }
;             bf16x8 vf[2][4];
;     ...
;             ATT_LOADV(vf[0], 0); if (!DEEP) ATT_LOADV(vf[1], 1);
;             __builtin_amdgcn_sched_barrier(0);
;             if (MODE != 1) {
;                 float mx = fmaxf(s0[0], s1[0]);
; #pragma unroll
;                 for (int r = 1; r < 16; ++r) mx = fmaxf(fmaxf(mx, s0[r]), s1[r]);
;                 { float a, b; swap32(mx, a, b); mx = fmaxf(a, b); }
;                 const bool first = (i == 0);
;                 if (first || __any(mx > 8.0f)) {
;                     const float dl = first ? mx : fmaxf(mx, 0.f);
;                     mhat += dl;
; #pragma unroll
;                     for (int r = 0; r < 16; ++r) { s0[r] -= dl; s1[r] -= dl; negm[r] = -mhat; }
;                     if (DEEP && QKFIRST && hf == 0 && (ATT_TILE(i0 + UNR - 1) <= my_last)) {
; #pragma unroll
;                         for (int r = 0; r < 16; ++r) { sq[UNR - 1][0][r] -= dl; sq[UNR - 1][1][r] -= dl; }
;                     }
;                     if (!first) {
;                         const float alpha = __builtin_amdgcn_exp2f(-dl);
;                         l_run *= alpha;
; #pragma unroll
;                         for (int i2 = 0; i2 < NDB; ++i2)
; #pragma unroll
.LBB0_575:
	s_mul_i32 s7, s5, 0x6c00
	v_add_u32_e32 v221, s7, v219
	ds_read_b128 v[148:151], v221
	ds_read_b128 v[152:155], v221 offset:4608
	ds_read_b128 v[156:159], v221 offset:32
	ds_read_b128 v[160:163], v221 offset:4640
	ds_read_b128 v[164:167], v221 offset:64
	ds_read_b128 v[168:171], v221 offset:4672
	ds_read_b128 v[172:175], v221 offset:96
	ds_read_b128 v[176:179], v221 offset:4704
	s_setprio 1
	s_waitcnt lgkmcnt(7)
	v_mfma_f32_32x32x16_bf16 v[80:95], v[148:151], v[120:123], v[64:79]
	ds_read_b128 v[240:243], v221 offset:9216
	s_waitcnt lgkmcnt(7)
	v_mfma_f32_32x32x16_bf16 v[96:111], v[152:155], v[120:123], v[64:79]
	ds_read_b128 v[244:247], v221 offset:13824
	s_waitcnt lgkmcnt(7)
	v_mfma_f32_32x32x16_bf16 v[80:95], v[156:159], v[124:127], v[80:95]
	ds_read_b128 v[248:251], v221 offset:18432
	s_waitcnt lgkmcnt(7)
	v_mfma_f32_32x32x16_bf16 v[96:111], v[160:163], v[124:127], v[96:111]
	ds_read_b128 v[148:151], v221 offset:23040
	s_waitcnt lgkmcnt(7)
	v_mfma_f32_32x32x16_bf16 v[80:95], v[164:167], v[128:131], v[80:95]
	ds_read_b128 v[152:155], v221 offset:9248
	s_waitcnt lgkmcnt(7)
	v_mfma_f32_32x32x16_bf16 v[96:111], v[168:171], v[128:131], v[96:111]
	ds_read_b128 v[156:159], v221 offset:13856
	s_waitcnt lgkmcnt(7)
	v_mfma_f32_32x32x16_bf16 v[80:95], v[172:175], v[132:135], v[80:95]
	ds_read_b128 v[160:163], v221 offset:18464
	s_waitcnt lgkmcnt(7)
	v_mfma_f32_32x32x16_bf16 v[96:111], v[176:179], v[132:135], v[96:111]
	ds_read_b128 v[164:167], v221 offset:23072
	s_setprio 0
	s_nop 6
	v_max3_f32 v222, v80, v81, v82
	s_nop 1
	v_max3_f32 v223, v96, v97, v98
	v_max3_f32 v222, v222, v83, v84
	v_max3_f32 v223, v223, v99, v100
	v_max3_f32 v222, v222, v85, v86
	v_max3_f32 v223, v223, v101, v102
	v_max3_f32 v222, v222, v87, v88
	v_max3_f32 v223, v223, v103, v104
	v_max3_f32 v222, v222, v89, v90
	v_max3_f32 v223, v223, v105, v106
	v_max3_f32 v222, v222, v91, v92
	v_max3_f32 v223, v223, v107, v108
	v_max3_f32 v222, v222, v93, v94
	v_max3_f32 v223, v223, v109, v110
	v_max3_f32 v222, v222, v95, v111
	v_max_f32_e32 v222, v222, v223
	v_mov_b32_e32 v223, v222
	s_nop 1
	v_permlane32_swap_b32_e32 v222, v223
	v_max_f32_e32 v222, v222, v223
	v_cmp_lt_f32_e32 vcc, s26, v222
	s_cbranch_vccnz .Ldf_rare0
.Ldf_back0:
	v_exp_f32_e32 v80, v80
	v_exp_f32_e32 v81, v81
	v_exp_f32_e32 v82, v82
	v_add_f32_e32 v223, v80, v81
	v_exp_f32_e32 v83, v83
	v_add_f32_e32 v223, v223, v82
	v_exp_f32_e32 v84, v84
	v_add_f32_e32 v223, v223, v83
	v_exp_f32_e32 v85, v85
	v_add_f32_e32 v223, v223, v84
	v_exp_f32_e32 v86, v86
	v_add_f32_e32 v223, v223, v85
	v_exp_f32_e32 v87, v87
	v_add_f32_e32 v223, v223, v86
	v_add_f32_e32 v223, v223, v87
	v_cvt_pk_bf16_f32 v80, v80, v81
	v_cvt_pk_bf16_f32 v81, v82, v83
	v_cvt_pk_bf16_f32 v82, v84, v85
	v_cvt_pk_bf16_f32 v83, v86, v87
	v_exp_f32_e32 v88, v88
	v_exp_f32_e32 v89, v89
	v_exp_f32_e32 v90, v90
	v_add_f32_e32 v223, v223, v88
	v_exp_f32_e32 v91, v91
	v_add_f32_e32 v223, v223, v89
	v_exp_f32_e32 v92, v92
	v_add_f32_e32 v223, v223, v90
	v_exp_f32_e32 v93, v93
	v_add_f32_e32 v223, v223, v91
	v_exp_f32_e32 v94, v94
	v_add_f32_e32 v223, v223, v92
	v_exp_f32_e32 v95, v95
	v_add_f32_e32 v223, v223, v93
	v_add_f32_e32 v223, v223, v94
	v_add_f32_e32 v223, v223, v95
	v_cvt_pk_bf16_f32 v84, v88, v89
	v_cvt_pk_bf16_f32 v85, v90, v91
	v_cvt_pk_bf16_f32 v86, v92, v93
	v_cvt_pk_bf16_f32 v87, v94, v95
	v_exp_f32_e32 v96, v96
	v_exp_f32_e32 v97, v97
	v_exp_f32_e32 v98, v98
	v_add_f32_e32 v224, v96, v97
	v_exp_f32_e32 v99, v99
	v_add_f32_e32 v224, v224, v98
	v_exp_f32_e32 v100, v100
	v_add_f32_e32 v224, v224, v99
	v_exp_f32_e32 v101, v101
	v_add_f32_e32 v224, v224, v100
	v_exp_f32_e32 v102, v102
	v_add_f32_e32 v224, v224, v101
	v_exp_f32_e32 v103, v103
	v_add_f32_e32 v224, v224, v102
	v_add_f32_e32 v224, v224, v103
	v_cvt_pk_bf16_f32 v88, v96, v97
	v_cvt_pk_bf16_f32 v89, v98, v99
	v_cvt_pk_bf16_f32 v90, v100, v101
	v_cvt_pk_bf16_f32 v91, v102, v103
	v_exp_f32_e32 v104, v104
	v_exp_f32_e32 v105, v105
	v_exp_f32_e32 v106, v106
	v_add_f32_e32 v224, v224, v104
	v_exp_f32_e32 v107, v107
	v_add_f32_e32 v224, v224, v105
	v_exp_f32_e32 v108, v108
	v_add_f32_e32 v224, v224, v106
	v_exp_f32_e32 v109, v109
	v_add_f32_e32 v224, v224, v107
	v_exp_f32_e32 v110, v110
	v_add_f32_e32 v224, v224, v108
	v_exp_f32_e32 v111, v111
	v_add_f32_e32 v224, v224, v109
	v_add_f32_e32 v224, v224, v110
	v_add_f32_e32 v224, v224, v111
	v_cvt_pk_bf16_f32 v92, v104, v105
	v_cvt_pk_bf16_f32 v93, v106, v107
	v_cvt_pk_bf16_f32 v94, v108, v109
	v_cvt_pk_bf16_f32 v95, v110, v111
	v_add_f32_e32 v223, v223, v224
	v_add_f32_e32 v203, v203, v223
	s_setprio 1
	s_waitcnt lgkmcnt(7)
	v_mfma_f32_32x32x16_bf16 v[48:63], v[240:243], v[80:83], v[48:63]
	ds_read_b128 v[168:171], v221 offset:9280
	s_waitcnt lgkmcnt(7)
	v_mfma_f32_32x32x16_bf16 v[32:47], v[244:247], v[80:83], v[32:47]
	ds_read_b128 v[172:175], v221 offset:13888
	s_waitcnt lgkmcnt(7)
	v_mfma_f32_32x32x16_bf16 v[0:15], v[248:251], v[80:83], v[0:15]
	ds_read_b128 v[176:179], v221 offset:18496
	s_waitcnt lgkmcnt(7)
	v_mfma_f32_32x32x16_bf16 v[16:31], v[148:151], v[80:83], v[16:31]
	ds_read_b128 v[240:243], v221 offset:23104
	s_waitcnt lgkmcnt(7)
	v_mfma_f32_32x32x16_bf16 v[48:63], v[152:155], v[84:87], v[48:63]
	ds_read_b128 v[244:247], v221 offset:9312
	s_waitcnt lgkmcnt(7)
	v_mfma_f32_32x32x16_bf16 v[32:47], v[156:159], v[84:87], v[32:47]
	ds_read_b128 v[248:251], v221 offset:13920
	s_waitcnt lgkmcnt(7)
	v_mfma_f32_32x32x16_bf16 v[0:15], v[160:163], v[84:87], v[0:15]
	ds_read_b128 v[148:151], v221 offset:18528
	s_waitcnt lgkmcnt(7)
	v_mfma_f32_32x32x16_bf16 v[16:31], v[164:167], v[84:87], v[16:31]
	ds_read_b128 v[152:155], v221 offset:23136
	s_waitcnt lgkmcnt(7)
	v_mfma_f32_32x32x16_bf16 v[48:63], v[168:171], v[88:91], v[48:63]
	s_waitcnt lgkmcnt(6)
	v_mfma_f32_32x32x16_bf16 v[32:47], v[172:175], v[88:91], v[32:47]
	s_waitcnt lgkmcnt(5)
	v_mfma_f32_32x32x16_bf16 v[0:15], v[176:179], v[88:91], v[0:15]
	s_waitcnt lgkmcnt(4)
	v_mfma_f32_32x32x16_bf16 v[16:31], v[240:243], v[88:91], v[16:31]
	s_waitcnt lgkmcnt(3)
	v_mfma_f32_32x32x16_bf16 v[48:63], v[244:247], v[92:95], v[48:63]
	s_waitcnt lgkmcnt(2)
	v_mfma_f32_32x32x16_bf16 v[32:47], v[248:251], v[92:95], v[32:47]
	s_waitcnt lgkmcnt(1)
	v_mfma_f32_32x32x16_bf16 v[0:15], v[148:151], v[92:95], v[0:15]
	s_waitcnt lgkmcnt(0)
	v_mfma_f32_32x32x16_bf16 v[16:31], v[152:155], v[92:95], v[16:31]
	s_setprio 0
	s_cmp_ge_u32 s6, s31
	s_cbranch_scc1 .LBB0_570
